# final output stores (P8 round-0 y and P9) default-cached instead of nt
# speedup vs baseline: 1.0045x; 1.0014x over previous
.LBB0_1667:
	s_or_b64 exec, exec, s[26:27]
	v_readlane_b32 s0, v253, 6
	v_readlane_b32 s12, v253, 18
	v_readlane_b32 s13, v253, 19
	s_waitcnt lgkmcnt(0)
	s_waitcnt lgkmcnt(0)
	s_barrier
	v_lshl_add_u64 v[128:129], v[156:157], 2, s[12:13]
	global_load_dwordx4 v[132:135], v[128:129], off
	global_load_dwordx4 v[136:139], v[128:129], off offset:64
	global_load_dwordx4 v[140:143], v[128:129], off offset:512
	global_load_dwordx4 v[160:163], v[128:129], off offset:576
	ds_read_b32 v164, v223 offset:0
	ds_read_b32 v166, v223 offset:64
	ds_read_b32 v168, v223 offset:128
	ds_read_b32 v170, v223 offset:192
	ds_read_b32 v172, v223 offset:512
	ds_read_b32 v174, v223 offset:576
	ds_read_b32 v176, v223 offset:640
	ds_read_b32 v178, v223 offset:704
	v_lshlrev_b32_e32 v180, 2, v148
	s_waitcnt vmcnt(0) lgkmcnt(0)
	v_mov_b32_e32 v181, v180
	v_pk_mul_f32 v[124:125], v[124:125], v[164:165] op_sel_hi:[1,0]
	v_pk_mul_f32 v[126:127], v[126:127], v[164:165] op_sel_hi:[1,0]
	v_pk_mul_f32 v[124:125], v[132:133], v[124:125]
	v_pk_mul_f32 v[126:127], v[134:135], v[126:127]
	global_store_dwordx4 v181, v[124:127], s[8:9] offset:0
	v_pk_mul_f32 v[120:121], v[120:121], v[164:165] op_sel_hi:[1,0]
	v_pk_mul_f32 v[122:123], v[122:123], v[164:165] op_sel_hi:[1,0]
	v_pk_mul_f32 v[120:121], v[136:137], v[120:121]
	v_pk_mul_f32 v[122:123], v[138:139], v[122:123]
	global_store_dwordx4 v181, v[120:123], s[8:9] offset:64
	v_pk_mul_f32 v[116:117], v[116:117], v[164:165] op_sel_hi:[1,0]
	v_pk_mul_f32 v[118:119], v[118:119], v[164:165] op_sel_hi:[1,0]
	v_pk_mul_f32 v[116:117], v[140:141], v[116:117]
	v_pk_mul_f32 v[118:119], v[142:143], v[118:119]
	global_store_dwordx4 v181, v[116:119], s[8:9] offset:512
	v_pk_mul_f32 v[108:109], v[108:109], v[164:165] op_sel_hi:[1,0]
	v_pk_mul_f32 v[110:111], v[110:111], v[164:165] op_sel_hi:[1,0]
	v_pk_mul_f32 v[108:109], v[160:161], v[108:109]
	v_pk_mul_f32 v[110:111], v[162:163], v[110:111]
	global_store_dwordx4 v181, v[108:111], s[8:9] offset:576
	v_add_u32_e32 v182, 0x20000, v180
	v_pk_mul_f32 v[112:113], v[112:113], v[166:167] op_sel_hi:[1,0]
	v_pk_mul_f32 v[114:115], v[114:115], v[166:167] op_sel_hi:[1,0]
	v_pk_mul_f32 v[112:113], v[132:133], v[112:113]
	v_pk_mul_f32 v[114:115], v[134:135], v[114:115]
	global_store_dwordx4 v182, v[112:115], s[8:9] offset:0
	v_pk_mul_f32 v[104:105], v[104:105], v[166:167] op_sel_hi:[1,0]
	v_pk_mul_f32 v[106:107], v[106:107], v[166:167] op_sel_hi:[1,0]
	v_pk_mul_f32 v[104:105], v[136:137], v[104:105]
	v_pk_mul_f32 v[106:107], v[138:139], v[106:107]
	global_store_dwordx4 v182, v[104:107], s[8:9] offset:64
	v_pk_mul_f32 v[100:101], v[100:101], v[166:167] op_sel_hi:[1,0]
	v_pk_mul_f32 v[102:103], v[102:103], v[166:167] op_sel_hi:[1,0]
	v_pk_mul_f32 v[100:101], v[140:141], v[100:101]
	v_pk_mul_f32 v[102:103], v[142:143], v[102:103]
	global_store_dwordx4 v182, v[100:103], s[8:9] offset:512
	v_pk_mul_f32 v[92:93], v[92:93], v[166:167] op_sel_hi:[1,0]
	v_pk_mul_f32 v[94:95], v[94:95], v[166:167] op_sel_hi:[1,0]
	v_pk_mul_f32 v[92:93], v[160:161], v[92:93]
	v_pk_mul_f32 v[94:95], v[162:163], v[94:95]
	global_store_dwordx4 v182, v[92:95], s[8:9] offset:576
	v_add_u32_e32 v181, 0x40000, v180
	v_pk_mul_f32 v[96:97], v[96:97], v[168:169] op_sel_hi:[1,0]
	v_pk_mul_f32 v[98:99], v[98:99], v[168:169] op_sel_hi:[1,0]
	v_pk_mul_f32 v[96:97], v[132:133], v[96:97]
	v_pk_mul_f32 v[98:99], v[134:135], v[98:99]
	global_store_dwordx4 v181, v[96:99], s[8:9] offset:0
	v_pk_mul_f32 v[88:89], v[88:89], v[168:169] op_sel_hi:[1,0]
	v_pk_mul_f32 v[90:91], v[90:91], v[168:169] op_sel_hi:[1,0]
	v_pk_mul_f32 v[88:89], v[136:137], v[88:89]
	v_pk_mul_f32 v[90:91], v[138:139], v[90:91]
	global_store_dwordx4 v181, v[88:91], s[8:9] offset:64
	v_pk_mul_f32 v[84:85], v[84:85], v[168:169] op_sel_hi:[1,0]
	v_pk_mul_f32 v[86:87], v[86:87], v[168:169] op_sel_hi:[1,0]
	v_pk_mul_f32 v[84:85], v[140:141], v[84:85]
	v_pk_mul_f32 v[86:87], v[142:143], v[86:87]
	global_store_dwordx4 v181, v[84:87], s[8:9] offset:512
	v_pk_mul_f32 v[76:77], v[76:77], v[168:169] op_sel_hi:[1,0]
	v_pk_mul_f32 v[78:79], v[78:79], v[168:169] op_sel_hi:[1,0]
	v_pk_mul_f32 v[76:77], v[160:161], v[76:77]
	v_pk_mul_f32 v[78:79], v[162:163], v[78:79]
	global_store_dwordx4 v181, v[76:79], s[8:9] offset:576
	v_add_u32_e32 v182, 0x60000, v180
	v_pk_mul_f32 v[80:81], v[80:81], v[170:171] op_sel_hi:[1,0]
	v_pk_mul_f32 v[82:83], v[82:83], v[170:171] op_sel_hi:[1,0]
	v_pk_mul_f32 v[80:81], v[132:133], v[80:81]
	v_pk_mul_f32 v[82:83], v[134:135], v[82:83]
	global_store_dwordx4 v182, v[80:83], s[8:9] offset:0
	v_pk_mul_f32 v[72:73], v[72:73], v[170:171] op_sel_hi:[1,0]
	v_pk_mul_f32 v[74:75], v[74:75], v[170:171] op_sel_hi:[1,0]
	v_pk_mul_f32 v[72:73], v[136:137], v[72:73]
	v_pk_mul_f32 v[74:75], v[138:139], v[74:75]
	global_store_dwordx4 v182, v[72:75], s[8:9] offset:64
	v_pk_mul_f32 v[68:69], v[68:69], v[170:171] op_sel_hi:[1,0]
	v_pk_mul_f32 v[70:71], v[70:71], v[170:171] op_sel_hi:[1,0]
	v_pk_mul_f32 v[68:69], v[140:141], v[68:69]
	v_pk_mul_f32 v[70:71], v[142:143], v[70:71]
	global_store_dwordx4 v182, v[68:71], s[8:9] offset:512
	v_pk_mul_f32 v[64:65], v[64:65], v[170:171] op_sel_hi:[1,0]
	v_pk_mul_f32 v[66:67], v[66:67], v[170:171] op_sel_hi:[1,0]
	v_pk_mul_f32 v[64:65], v[160:161], v[64:65]
	v_pk_mul_f32 v[66:67], v[162:163], v[66:67]
	global_store_dwordx4 v182, v[64:67], s[8:9] offset:576
	v_add_u32_e32 v181, 0x100000, v180
	v_pk_mul_f32 v[60:61], v[60:61], v[172:173] op_sel_hi:[1,0]
	v_pk_mul_f32 v[62:63], v[62:63], v[172:173] op_sel_hi:[1,0]
	v_pk_mul_f32 v[60:61], v[132:133], v[60:61]
	v_pk_mul_f32 v[62:63], v[134:135], v[62:63]
	global_store_dwordx4 v181, v[60:63], s[8:9] offset:0
	v_pk_mul_f32 v[56:57], v[56:57], v[172:173] op_sel_hi:[1,0]
	v_pk_mul_f32 v[58:59], v[58:59], v[172:173] op_sel_hi:[1,0]
	v_pk_mul_f32 v[56:57], v[136:137], v[56:57]
	v_pk_mul_f32 v[58:59], v[138:139], v[58:59]
	global_store_dwordx4 v181, v[56:59], s[8:9] offset:64
	v_pk_mul_f32 v[52:53], v[52:53], v[172:173] op_sel_hi:[1,0]
	v_pk_mul_f32 v[54:55], v[54:55], v[172:173] op_sel_hi:[1,0]
	v_pk_mul_f32 v[52:53], v[140:141], v[52:53]
	v_pk_mul_f32 v[54:55], v[142:143], v[54:55]
	global_store_dwordx4 v181, v[52:55], s[8:9] offset:512
	v_pk_mul_f32 v[44:45], v[44:45], v[172:173] op_sel_hi:[1,0]
	v_pk_mul_f32 v[46:47], v[46:47], v[172:173] op_sel_hi:[1,0]
	v_pk_mul_f32 v[44:45], v[160:161], v[44:45]
	v_pk_mul_f32 v[46:47], v[162:163], v[46:47]
	global_store_dwordx4 v181, v[44:47], s[8:9] offset:576
	v_add_u32_e32 v182, 0x120000, v180
	v_pk_mul_f32 v[48:49], v[48:49], v[174:175] op_sel_hi:[1,0]
	v_pk_mul_f32 v[50:51], v[50:51], v[174:175] op_sel_hi:[1,0]
	v_pk_mul_f32 v[48:49], v[132:133], v[48:49]
	v_pk_mul_f32 v[50:51], v[134:135], v[50:51]
	global_store_dwordx4 v182, v[48:51], s[8:9] offset:0
	v_pk_mul_f32 v[40:41], v[40:41], v[174:175] op_sel_hi:[1,0]
	v_pk_mul_f32 v[42:43], v[42:43], v[174:175] op_sel_hi:[1,0]
	v_pk_mul_f32 v[40:41], v[136:137], v[40:41]
	v_pk_mul_f32 v[42:43], v[138:139], v[42:43]
	global_store_dwordx4 v182, v[40:43], s[8:9] offset:64
	v_pk_mul_f32 v[36:37], v[36:37], v[174:175] op_sel_hi:[1,0]
	v_pk_mul_f32 v[38:39], v[38:39], v[174:175] op_sel_hi:[1,0]
	v_pk_mul_f32 v[36:37], v[140:141], v[36:37]
	v_pk_mul_f32 v[38:39], v[142:143], v[38:39]
	global_store_dwordx4 v182, v[36:39], s[8:9] offset:512
	v_pk_mul_f32 v[28:29], v[28:29], v[174:175] op_sel_hi:[1,0]
	v_pk_mul_f32 v[30:31], v[30:31], v[174:175] op_sel_hi:[1,0]
	v_pk_mul_f32 v[28:29], v[160:161], v[28:29]
	v_pk_mul_f32 v[30:31], v[162:163], v[30:31]
	global_store_dwordx4 v182, v[28:31], s[8:9] offset:576
	v_add_u32_e32 v181, 0x140000, v180
	v_pk_mul_f32 v[32:33], v[32:33], v[176:177] op_sel_hi:[1,0]
	v_pk_mul_f32 v[34:35], v[34:35], v[176:177] op_sel_hi:[1,0]
	v_pk_mul_f32 v[32:33], v[132:133], v[32:33]
	v_pk_mul_f32 v[34:35], v[134:135], v[34:35]
	global_store_dwordx4 v181, v[32:35], s[8:9] offset:0
	v_pk_mul_f32 v[24:25], v[24:25], v[176:177] op_sel_hi:[1,0]
	v_pk_mul_f32 v[26:27], v[26:27], v[176:177] op_sel_hi:[1,0]
	v_pk_mul_f32 v[24:25], v[136:137], v[24:25]
	v_pk_mul_f32 v[26:27], v[138:139], v[26:27]
	global_store_dwordx4 v181, v[24:27], s[8:9] offset:64
	v_pk_mul_f32 v[20:21], v[20:21], v[176:177] op_sel_hi:[1,0]
	v_pk_mul_f32 v[22:23], v[22:23], v[176:177] op_sel_hi:[1,0]
	v_pk_mul_f32 v[20:21], v[140:141], v[20:21]
	v_pk_mul_f32 v[22:23], v[142:143], v[22:23]
	global_store_dwordx4 v181, v[20:23], s[8:9] offset:512
	v_pk_mul_f32 v[12:13], v[12:13], v[176:177] op_sel_hi:[1,0]
	v_pk_mul_f32 v[14:15], v[14:15], v[176:177] op_sel_hi:[1,0]
	v_pk_mul_f32 v[12:13], v[160:161], v[12:13]
	v_pk_mul_f32 v[14:15], v[162:163], v[14:15]
	global_store_dwordx4 v181, v[12:15], s[8:9] offset:576
	v_add_u32_e32 v182, 0x160000, v180
	v_pk_mul_f32 v[16:17], v[16:17], v[178:179] op_sel_hi:[1,0]
	v_pk_mul_f32 v[18:19], v[18:19], v[178:179] op_sel_hi:[1,0]
	v_pk_mul_f32 v[16:17], v[132:133], v[16:17]
	v_pk_mul_f32 v[18:19], v[134:135], v[18:19]
	global_store_dwordx4 v182, v[16:19], s[8:9] offset:0
	v_pk_mul_f32 v[8:9], v[8:9], v[178:179] op_sel_hi:[1,0]
	v_pk_mul_f32 v[10:11], v[10:11], v[178:179] op_sel_hi:[1,0]
	v_pk_mul_f32 v[8:9], v[136:137], v[8:9]
	v_pk_mul_f32 v[10:11], v[138:139], v[10:11]
	global_store_dwordx4 v182, v[8:11], s[8:9] offset:64
	v_pk_mul_f32 v[4:5], v[4:5], v[178:179] op_sel_hi:[1,0]
	v_pk_mul_f32 v[6:7], v[6:7], v[178:179] op_sel_hi:[1,0]
	v_pk_mul_f32 v[4:5], v[140:141], v[4:5]
	v_pk_mul_f32 v[6:7], v[142:143], v[6:7]
	global_store_dwordx4 v182, v[4:7], s[8:9] offset:512
	v_pk_mul_f32 v[0:1], v[0:1], v[178:179] op_sel_hi:[1,0]
	v_pk_mul_f32 v[2:3], v[2:3], v[178:179] op_sel_hi:[1,0]
	v_pk_mul_f32 v[0:1], v[160:161], v[0:1]
	v_pk_mul_f32 v[2:3], v[162:163], v[2:3]
	global_store_dwordx4 v182, v[0:3], s[8:9] offset:576
	s_branch .LBB0_1668

.LBB0_1726:
	global_load_dwordx4 v[34:37], v[60:61], off
	s_waitcnt vmcnt(0)
	v_fmamk_f32 v32, v32, 0x3a000000, v56
	v_mul_f32_e32 v33, 0x4b800000, v32
	v_cmp_gt_f32_e32 vcc, s18, v32
	s_add_i32 s0, s0, s4
	s_add_u32 s6, s6, s8
	v_cndmask_b32_e32 v32, v32, v33, vcc
	v_rsq_f32_e32 v32, v32
	s_addc_u32 s7, s7, s9
	s_cmpk_lt_i32 s0, 0x2800
	v_mul_f32_e32 v33, 0x45800000, v32
	v_cndmask_b32_e32 v32, v32, v33, vcc
	v_pk_mul_f32 v[28:29], v[32:33], v[28:29] op_sel_hi:[0,1]
	v_pk_mul_f32 v[30:31], v[32:33], v[30:31] op_sel_hi:[0,1]
	v_pk_mul_f32 v[26:27], v[32:33], v[26:27] op_sel_hi:[0,1]
	v_pk_mul_f32 v[24:25], v[32:33], v[24:25] op_sel_hi:[0,1]
	v_pk_mul_f32 v[22:23], v[32:33], v[22:23] op_sel_hi:[0,1]
	v_pk_mul_f32 v[20:21], v[32:33], v[20:21] op_sel_hi:[0,1]
	v_pk_mul_f32 v[18:19], v[32:33], v[18:19] op_sel_hi:[0,1]
	v_pk_mul_f32 v[16:17], v[32:33], v[16:17] op_sel_hi:[0,1]
	v_pk_mul_f32 v[14:15], v[32:33], v[14:15] op_sel_hi:[0,1]
	v_pk_mul_f32 v[12:13], v[32:33], v[12:13] op_sel_hi:[0,1]
	v_pk_mul_f32 v[10:11], v[32:33], v[10:11] op_sel_hi:[0,1]
	v_pk_mul_f32 v[8:9], v[32:33], v[8:9] op_sel_hi:[0,1]
	v_pk_mul_f32 v[6:7], v[32:33], v[6:7] op_sel_hi:[0,1]
	v_pk_mul_f32 v[4:5], v[32:33], v[4:5] op_sel_hi:[0,1]
	v_pk_mul_f32 v[2:3], v[32:33], v[2:3] op_sel_hi:[0,1]
	v_pk_mul_f32 v[0:1], v[32:33], v[0:1] op_sel_hi:[0,1]
	v_pk_mul_f32 v[30:31], v[30:31], v[36:37]
	v_pk_mul_f32 v[28:29], v[28:29], v[34:35]
	global_store_dwordx4 v[70:71], v[28:31], off offset:-4096
	global_load_dwordx4 v[28:31], v[60:61], off offset:1024
	s_waitcnt vmcnt(0)
	v_pk_mul_f32 v[24:25], v[24:25], v[28:29]
	v_pk_mul_f32 v[26:27], v[26:27], v[30:31]
	global_store_dwordx4 v[70:71], v[24:27], off offset:-3072
	global_load_dwordx4 v[24:27], v[60:61], off offset:2048
	s_waitcnt vmcnt(0)
	v_pk_mul_f32 v[20:21], v[20:21], v[24:25]
	v_pk_mul_f32 v[22:23], v[22:23], v[26:27]
	global_store_dwordx4 v[70:71], v[20:23], off offset:-2048
	global_load_dwordx4 v[20:23], v[60:61], off offset:3072
	s_waitcnt vmcnt(0)
	v_pk_mul_f32 v[16:17], v[16:17], v[20:21]
	v_pk_mul_f32 v[18:19], v[18:19], v[22:23]
	global_store_dwordx4 v[70:71], v[16:19], off offset:-1024
	global_load_dwordx4 v[16:19], v[62:63], off
	s_waitcnt vmcnt(0)
	v_pk_mul_f32 v[12:13], v[12:13], v[16:17]
	v_pk_mul_f32 v[14:15], v[14:15], v[18:19]
	global_store_dwordx4 v[70:71], v[12:15], off
	global_load_dwordx4 v[12:15], v[64:65], off
	s_waitcnt vmcnt(0)
	v_pk_mul_f32 v[8:9], v[8:9], v[12:13]
	v_pk_mul_f32 v[10:11], v[10:11], v[14:15]
	global_store_dwordx4 v[70:71], v[8:11], off offset:1024
	global_load_dwordx4 v[8:11], v[66:67], off
	s_waitcnt vmcnt(0)
	v_pk_mul_f32 v[4:5], v[4:5], v[8:9]
	v_pk_mul_f32 v[6:7], v[6:7], v[10:11]
	global_store_dwordx4 v[70:71], v[4:7], off offset:2048
	global_load_dwordx4 v[4:7], v[68:69], off
	s_waitcnt vmcnt(0)
	v_pk_mul_f32 v[0:1], v[0:1], v[4:5]
	v_pk_mul_f32 v[2:3], v[2:3], v[6:7]
	global_store_dwordx4 v[70:71], v[0:3], off offset:3072
	v_lshl_add_u64 v[70:71], v[70:71], 0, s[10:11]
	s_cbranch_scc0 .LBB0_1731
